# v sweep: adjacent counted waits merged pairwise into the stricter one (11 fewer s_waitcnt per step), on-the-fly LN packed ops spaced by independent instructions instead of s_nop
# speedup vs baseline: 1.0030x; 1.0030x over previous
.Lvsw_skip_gb:
	v_readlane_b32 s100, v252, s39
	v_readlane_b32 s101, v253, s39
	v_ashrrev_i32_e32 v139, 31, v138
	v_lshl_add_u32 v173, s18, 1, v145
	s_lshl_b32 s18, s11, 7
	v_lshlrev_b64 v[138:139], 10, v[138:139]
	v_lshl_add_u64 v[138:139], v[138:139], 0, s[18:19]
	s_lshl_b32 s18, s11, 21
	s_waitcnt lgkmcnt(6)
	v_lshlrev_b32_sdwa v72, v141, v153 dst_sel:DWORD dst_unused:UNUSED_PAD src0_sel:DWORD src1_sel:WORD_0
	s_waitcnt vmcnt(6)
	v_cvt_pk_f32_fp8_e32 v[36:37], v28
	v_cvt_pk_f32_fp8_sdwa v[38:39], v28 src0_sel:WORD_1
	v_cvt_pk_f32_fp8_e32 v[40:41], v29
	v_cvt_pk_f32_fp8_sdwa v[28:29], v29 src0_sel:WORD_1
	v_cvt_pk_f32_fp8_e32 v[42:43], v30
	v_cvt_pk_f32_fp8_sdwa v[44:45], v30 src0_sel:WORD_1
	v_cvt_pk_f32_fp8_e32 v[48:49], v31
	v_cvt_pk_f32_fp8_sdwa v[50:51], v31 src0_sel:WORD_1
	v_lshl_add_u64 v[162:163], v[32:33], 0, s[18:19]
	v_cvt_pk_f32_fp8_e32 v[30:31], v20
	v_cvt_pk_f32_fp8_sdwa v[46:47], v20 src0_sel:WORD_1
	v_cvt_pk_f32_fp8_e32 v[52:53], v21
	v_cvt_pk_f32_fp8_sdwa v[54:55], v21 src0_sel:WORD_1
	v_cvt_pk_f32_fp8_e32 v[58:59], v22
	v_cvt_pk_f32_fp8_sdwa v[60:61], v22 src0_sel:WORD_1
	v_cvt_pk_f32_fp8_e32 v[68:69], v23
	v_cvt_pk_f32_fp8_sdwa v[70:71], v23 src0_sel:WORD_1
	v_lshl_add_u32 v154, s39, 8, v77
	v_or_b32_e32 v138, v138, v34
	v_lshl_add_u64 v[156:157], v[162:163], 0, v[72:73]
	v_lshlrev_b32_sdwa v72, v141, v146 dst_sel:DWORD dst_unused:UNUSED_PAD src0_sel:DWORD src1_sel:WORD_0
	s_waitcnt vmcnt(4)
	v_cvt_pk_f32_fp8_e32 v[20:21], v24
	v_cvt_pk_f32_fp8_sdwa v[22:23], v24 src0_sel:WORD_1
	v_cvt_pk_f32_fp8_e32 v[56:57], v25
	v_cvt_pk_f32_fp8_sdwa v[24:25], v25 src0_sel:WORD_1
	v_cvt_pk_f32_fp8_e32 v[62:63], v26
	v_cvt_pk_f32_fp8_sdwa v[64:65], v26 src0_sel:WORD_1
	v_cvt_pk_f32_fp8_e32 v[78:79], v27
	v_cvt_pk_f32_fp8_sdwa v[80:81], v27 src0_sel:WORD_1
	ds_read_u16 v175, v173
	ds_read_u16 v179, v173 offset:16
	ds_read_u16 v181, v173 offset:32
	ds_read_u16 v183, v173 offset:48
	ds_read_u16 v185, v173 offset:64
	ds_read_u16 v187, v173 offset:80
	ds_read_u16 v189, v173 offset:96
	ds_read_u16 v191, v173 offset:112
	ds_read_u16 v160, v154
	ds_read_u16 v161, v154 offset:16
	ds_read_u16 v169, v154 offset:32
	ds_read_u16 v174, v154 offset:48
	ds_read_u16 v180, v154 offset:64
	ds_read_u16 v182, v154 offset:80
	ds_read_u16 v184, v154 offset:96
	ds_read_u16 v186, v154 offset:112
	ds_read_u16 v153, v173 offset:128
	ds_read_u16 v188, v154 offset:128
	ds_read_u16 v190, v154 offset:144
	ds_read_u16 v192, v154 offset:160
	ds_read_u16 v193, v154 offset:176
	ds_read_u16 v195, v154 offset:192
	ds_read_u16 v197, v154 offset:208
	ds_read_u16 v199, v154 offset:224
	ds_read_u16 v201, v154 offset:240
	v_lshlrev_b64 v[154:155], 2, v[138:139]
	v_lshl_add_u64 v[138:139], v[138:139], 1, s[64:65]
	v_lshl_add_u64 v[158:159], v[162:163], 0, v[72:73]
	s_waitcnt lgkmcnt(14)
	v_lshlrev_b32_sdwa v72, v141, v151 dst_sel:DWORD dst_unused:UNUSED_PAD src0_sel:DWORD src1_sel:WORD_0
	v_cvt_pk_f32_fp8_e32 v[26:27], v12
	v_cvt_pk_f32_fp8_sdwa v[66:67], v12 src0_sel:WORD_1
	v_cvt_pk_f32_fp8_e32 v[82:83], v13
	v_cvt_pk_f32_fp8_sdwa v[12:13], v13 src0_sel:WORD_1
	v_cvt_pk_f32_fp8_e32 v[86:87], v14
	v_cvt_pk_f32_fp8_sdwa v[88:89], v14 src0_sel:WORD_1
	v_cvt_pk_f32_fp8_e32 v[92:93], v15
	v_cvt_pk_f32_fp8_sdwa v[94:95], v15 src0_sel:WORD_1
	ds_read_u16 v146, v173 offset:144
	ds_read_u16 v151, v173 offset:160
	v_lshl_add_u64 v[166:167], s[62:63], 0, v[154:155]
	global_load_dword v203, v[138:139], off
	v_lshlrev_b32_e32 v168, 16, v160
	v_lshlrev_b32_e32 v170, 16, v161
	v_lshl_add_u64 v[138:139], s[60:61], 0, v[154:155]
	global_load_dwordx4 v[154:157], v[156:157], off
	s_nop 0
	global_load_dwordx4 v[158:161], v[158:159], off
	v_lshl_add_u64 v[204:205], v[162:163], 0, v[72:73]
	v_lshlrev_b32_sdwa v72, v141, v152 dst_sel:DWORD dst_unused:UNUSED_PAD src0_sel:DWORD src1_sel:WORD_0
	v_lshlrev_b32_e32 v172, 16, v169
	v_pk_fma_f32 v[36:37], v[36:37], v[168:169], 0 op_sel_hi:[1,0,0]
	v_pk_fma_f32 v[38:39], v[38:39], v[168:169], 0 op_sel_hi:[1,0,0]
	v_pk_fma_f32 v[40:41], v[40:41], v[168:169], 0 op_sel_hi:[1,0,0]
	v_pk_fma_f32 v[28:29], v[28:29], v[168:169], 0 op_sel_hi:[1,0,0]
	v_pk_fma_f32 v[42:43], v[42:43], v[168:169], 0 op_sel_hi:[1,0,0]
	v_pk_fma_f32 v[44:45], v[44:45], v[168:169], 0 op_sel_hi:[1,0,0]
	v_pk_fma_f32 v[48:49], v[48:49], v[168:169], 0 op_sel_hi:[1,0,0]
	v_pk_fma_f32 v[50:51], v[50:51], v[168:169], 0 op_sel_hi:[1,0,0]
	v_lshl_add_u64 v[168:169], v[162:163], 0, v[72:73]
	v_lshlrev_b32_sdwa v72, v141, v147 dst_sel:DWORD dst_unused:UNUSED_PAD src0_sel:DWORD src1_sel:WORD_0
	s_waitcnt vmcnt(6)
	v_cvt_pk_f32_fp8_e32 v[14:15], v16
	v_cvt_pk_f32_fp8_sdwa v[84:85], v16 src0_sel:WORD_1
	v_cvt_pk_f32_fp8_e32 v[90:91], v17
	v_cvt_pk_f32_fp8_sdwa v[16:17], v17 src0_sel:WORD_1
	v_cvt_pk_f32_fp8_e32 v[96:97], v18
	v_cvt_pk_f32_fp8_sdwa v[98:99], v18 src0_sel:WORD_1
	v_cvt_pk_f32_fp8_e32 v[100:101], v19
	v_cvt_pk_f32_fp8_sdwa v[18:19], v19 src0_sel:WORD_1
	ds_read_u16 v152, v173 offset:176
	ds_read_u16 v147, v173 offset:192
	global_load_dwordx2 v[166:167], v[166:167], off
	v_pk_fma_f32 v[30:31], v[30:31], v[170:171], v[36:37] op_sel_hi:[1,0,1]
	v_pk_fma_f32 v[46:47], v[46:47], v[170:171], v[38:39] op_sel_hi:[1,0,1]
	v_pk_fma_f32 v[52:53], v[52:53], v[170:171], v[40:41] op_sel_hi:[1,0,1]
	v_pk_fma_f32 v[28:29], v[54:55], v[170:171], v[28:29] op_sel_hi:[1,0,1]
	v_pk_fma_f32 v[54:55], v[58:59], v[170:171], v[42:43] op_sel_hi:[1,0,1]
	v_pk_fma_f32 v[44:45], v[60:61], v[170:171], v[44:45] op_sel_hi:[1,0,1]
	v_pk_fma_f32 v[48:49], v[68:69], v[170:171], v[48:49] op_sel_hi:[1,0,1]
	v_pk_fma_f32 v[50:51], v[70:71], v[170:171], v[50:51] op_sel_hi:[1,0,1]
	global_load_dwordx4 v[36:39], v[204:205], off
	global_load_dwordx4 v[40:43], v[168:169], off
	v_lshl_add_u64 v[58:59], v[162:163], 0, v[72:73]
	v_lshlrev_b32_sdwa v72, v141, v148 dst_sel:DWORD dst_unused:UNUSED_PAD src0_sel:DWORD src1_sel:WORD_0
	s_waitcnt lgkmcnt(14)
	v_lshlrev_b32_e32 v174, 16, v174
	v_pk_fma_f32 v[20:21], v[20:21], v[172:173], v[30:31] op_sel_hi:[1,0,1]
	v_pk_fma_f32 v[22:23], v[22:23], v[172:173], v[46:47] op_sel_hi:[1,0,1]
	v_pk_fma_f32 v[30:31], v[56:57], v[172:173], v[52:53] op_sel_hi:[1,0,1]
	v_pk_fma_f32 v[24:25], v[24:25], v[172:173], v[28:29] op_sel_hi:[1,0,1]
	v_pk_fma_f32 v[28:29], v[62:63], v[172:173], v[54:55] op_sel_hi:[1,0,1]
	v_pk_fma_f32 v[44:45], v[64:65], v[172:173], v[44:45] op_sel_hi:[1,0,1]
	v_pk_fma_f32 v[46:47], v[78:79], v[172:173], v[48:49] op_sel_hi:[1,0,1]
	v_pk_fma_f32 v[48:49], v[80:81], v[172:173], v[50:51] op_sel_hi:[1,0,1]
	v_lshl_add_u64 v[50:51], v[162:163], 0, v[72:73]
	ds_read_u16 v148, v173 offset:208
	v_lshlrev_b32_sdwa v72, v141, v149 dst_sel:DWORD dst_unused:UNUSED_PAD src0_sel:DWORD src1_sel:WORD_0
	ds_read_u16 v149, v173 offset:224
	v_pk_fma_f32 v[20:21], v[26:27], v[174:175], v[20:21] op_sel_hi:[1,0,1]
	v_pk_fma_f32 v[26:27], v[82:83], v[174:175], v[30:31] op_sel_hi:[1,0,1]
	v_pk_fma_f32 v[12:13], v[12:13], v[174:175], v[24:25] op_sel_hi:[1,0,1]
	v_pk_fma_f32 v[24:25], v[86:87], v[174:175], v[28:29] op_sel_hi:[1,0,1]
	v_pk_fma_f32 v[28:29], v[88:89], v[174:175], v[44:45] op_sel_hi:[1,0,1]
	v_pk_fma_f32 v[30:31], v[92:93], v[174:175], v[46:47] op_sel_hi:[1,0,1]
	v_pk_fma_f32 v[52:53], v[94:95], v[174:175], v[48:49] op_sel_hi:[1,0,1]
	global_load_dwordx4 v[44:47], v[58:59], off
	s_nop 0
	global_load_dwordx4 v[48:51], v[50:51], off
	v_lshlrev_b32_e32 v180, 16, v180
	v_lshl_add_u64 v[54:55], v[162:163], 0, v[72:73]
	v_lshlrev_b32_sdwa v72, v141, v150 dst_sel:DWORD dst_unused:UNUSED_PAD src0_sel:DWORD src1_sel:WORD_0
	ds_read_u16 v150, v173 offset:240
	v_pk_fma_f32 v[12:13], v[16:17], v[180:181], v[12:13] op_sel_hi:[1,0,1]
	v_pk_fma_f32 v[16:17], v[96:97], v[180:181], v[24:25] op_sel_hi:[1,0,1]
	v_pk_fma_f32 v[24:25], v[98:99], v[180:181], v[28:29] op_sel_hi:[1,0,1]
	v_pk_fma_f32 v[18:19], v[18:19], v[180:181], v[52:53] op_sel_hi:[1,0,1]
	v_lshl_add_u64 v[28:29], v[162:163], 0, v[72:73]
	global_load_dwordx4 v[52:55], v[54:55], off
	s_nop 0
	global_load_dwordx4 v[56:59], v[28:29], off
	s_waitcnt vmcnt(10)
	v_cvt_pk_f32_fp8_e32 v[102:103], v4
	v_cvt_pk_f32_fp8_sdwa v[104:105], v4 src0_sel:WORD_1
	v_cvt_pk_f32_fp8_e32 v[106:107], v5
	v_cvt_pk_f32_fp8_sdwa v[4:5], v5 src0_sel:WORD_1
	v_cvt_pk_f32_fp8_e32 v[108:109], v6
	v_cvt_pk_f32_fp8_sdwa v[110:111], v6 src0_sel:WORD_1
	v_cvt_pk_f32_fp8_e32 v[114:115], v7
	v_cvt_pk_f32_fp8_sdwa v[116:117], v7 src0_sel:WORD_1
	v_cvt_pk_f32_fp8_e32 v[6:7], v8
	v_cvt_pk_f32_fp8_sdwa v[112:113], v8 src0_sel:WORD_1
	v_cvt_pk_f32_fp8_e32 v[118:119], v9
	v_cvt_pk_f32_fp8_sdwa v[8:9], v9 src0_sel:WORD_1
	v_cvt_pk_f32_fp8_e32 v[120:121], v10
	v_cvt_pk_f32_fp8_sdwa v[122:123], v10 src0_sel:WORD_1
	v_cvt_pk_f32_fp8_e32 v[124:125], v11
	v_cvt_pk_f32_fp8_sdwa v[10:11], v11 src0_sel:WORD_1
	v_cvt_pk_f32_fp8_e32 v[126:127], v0
	v_cvt_pk_f32_fp8_sdwa v[128:129], v0 src0_sel:WORD_1
	v_cvt_pk_f32_fp8_e32 v[130:131], v1
	v_cvt_pk_f32_fp8_sdwa v[0:1], v1 src0_sel:WORD_1
	s_and_b32 s18, s3, 0xe00000
	v_pk_fma_f32 v[22:23], v[66:67], v[174:175], v[22:23] op_sel_hi:[1,0,1]
	v_cvt_pk_f32_fp8_e32 v[132:133], v2
	v_cvt_pk_f32_fp8_sdwa v[134:135], v2 src0_sel:WORD_1
	v_cvt_pk_f32_fp8_e32 v[136:137], v3
	v_cvt_pk_f32_fp8_sdwa v[2:3], v3 src0_sel:WORD_1
	v_lshl_add_u64 v[164:165], v[32:33], 0, s[18:19]
	v_lshlrev_b32_e32 v182, 16, v182
	v_pk_fma_f32 v[14:15], v[14:15], v[180:181], v[20:21] op_sel_hi:[1,0,1]
	v_pk_fma_f32 v[20:21], v[84:85], v[180:181], v[22:23] op_sel_hi:[1,0,1]
	v_pk_fma_f32 v[22:23], v[90:91], v[180:181], v[26:27] op_sel_hi:[1,0,1]
	v_pk_fma_f32 v[26:27], v[100:101], v[180:181], v[30:31] op_sel_hi:[1,0,1]
	v_lshlrev_b32_e32 v72, 7, v175
	v_lshlrev_b32_e32 v184, 16, v184
	v_pk_fma_f32 v[4:5], v[4:5], v[182:183], v[12:13] op_sel_hi:[1,0,1]
	v_pk_fma_f32 v[12:13], v[108:109], v[182:183], v[16:17] op_sel_hi:[1,0,1]
	v_pk_fma_f32 v[16:17], v[110:111], v[182:183], v[24:25] op_sel_hi:[1,0,1]
	v_pk_fma_f32 v[24:25], v[114:115], v[182:183], v[26:27] op_sel_hi:[1,0,1]
	v_pk_fma_f32 v[18:19], v[116:117], v[182:183], v[18:19] op_sel_hi:[1,0,1]
	v_lshl_add_u64 v[26:27], v[164:165], 0, v[72:73]
	v_lshlrev_b32_e32 v72, 7, v179
	s_waitcnt lgkmcnt(14)
	v_lshlrev_b32_e32 v186, 16, v186
	v_pk_fma_f32 v[4:5], v[8:9], v[184:185], v[4:5] op_sel_hi:[1,0,1]
	v_pk_fma_f32 v[10:11], v[10:11], v[184:185], v[18:19] op_sel_hi:[1,0,1]
	v_lshl_add_u64 v[18:19], v[164:165], 0, v[72:73]
	v_lshlrev_b32_e32 v72, 7, v181
	v_pk_fma_f32 v[14:15], v[102:103], v[182:183], v[14:15] op_sel_hi:[1,0,1]
	v_pk_fma_f32 v[20:21], v[104:105], v[182:183], v[20:21] op_sel_hi:[1,0,1]
	v_pk_fma_f32 v[22:23], v[106:107], v[182:183], v[22:23] op_sel_hi:[1,0,1]
	v_pk_fma_f32 v[66:67], v[0:1], v[186:187], v[4:5] op_sel_hi:[1,0,1]
	v_lshl_add_u64 v[0:1], v[164:165], 0, v[72:73]
	v_lshlrev_b32_e32 v72, 7, v183
	v_pk_fma_f32 v[6:7], v[6:7], v[184:185], v[14:15] op_sel_hi:[1,0,1]
	v_pk_fma_f32 v[14:15], v[112:113], v[184:185], v[20:21] op_sel_hi:[1,0,1]
	v_pk_fma_f32 v[20:21], v[118:119], v[184:185], v[22:23] op_sel_hi:[1,0,1]
	v_pk_fma_f32 v[8:9], v[120:121], v[184:185], v[12:13] op_sel_hi:[1,0,1]
	v_pk_fma_f32 v[12:13], v[122:123], v[184:185], v[16:17] op_sel_hi:[1,0,1]
	v_pk_fma_f32 v[80:81], v[2:3], v[186:187], v[10:11] op_sel_hi:[1,0,1]
	v_lshl_add_u64 v[2:3], v[164:165], 0, v[72:73]
	v_lshlrev_b32_e32 v72, 7, v185
	v_pk_fma_f32 v[16:17], v[124:125], v[184:185], v[24:25] op_sel_hi:[1,0,1]
	v_pk_fma_f32 v[62:63], v[128:129], v[186:187], v[14:15] op_sel_hi:[1,0,1]
	v_pk_fma_f32 v[64:65], v[130:131], v[186:187], v[20:21] op_sel_hi:[1,0,1]
	v_pk_fma_f32 v[70:71], v[134:135], v[186:187], v[12:13] op_sel_hi:[1,0,1]
	global_load_dwordx4 v[28:31], v[26:27], off
	global_load_dwordx4 v[20:23], v[18:19], off
	s_nop 0
	global_load_dwordx4 v[24:27], v[0:1], off
	global_load_dwordx4 v[12:15], v[2:3], off
	v_lshl_add_u64 v[0:1], v[164:165], 0, v[72:73]
	v_lshlrev_b32_e32 v72, 7, v187
	v_lshl_add_u64 v[2:3], v[164:165], 0, v[72:73]
	v_lshlrev_b32_e32 v72, 7, v189
	v_pk_fma_f32 v[60:61], v[126:127], v[186:187], v[6:7] op_sel_hi:[1,0,1]
	v_pk_fma_f32 v[78:79], v[136:137], v[186:187], v[16:17] op_sel_hi:[1,0,1]
	global_load_dwordx4 v[16:19], v[0:1], off
	global_load_dwordx4 v[4:7], v[2:3], off
	v_lshl_add_u64 v[0:1], v[164:165], 0, v[72:73]
	v_lshlrev_b32_e32 v72, 7, v191
	v_lshl_add_u64 v[2:3], v[164:165], 0, v[72:73]
	v_pk_fma_f32 v[68:69], v[132:133], v[186:187], v[8:9] op_sel_hi:[1,0,1]
	global_load_dwordx4 v[8:11], v[0:1], off
	s_nop 0
	global_load_dwordx4 v[0:3], v[2:3], off
	s_waitcnt vmcnt(15)
	v_cvt_pk_f32_fp8_e32 v[82:83], v154
	v_cvt_pk_f32_fp8_sdwa v[84:85], v154 src0_sel:WORD_1
	v_cvt_pk_f32_fp8_e32 v[86:87], v155
	v_cvt_pk_f32_fp8_sdwa v[88:89], v155 src0_sel:WORD_1
	v_cvt_pk_f32_fp8_e32 v[90:91], v156
	v_cvt_pk_f32_fp8_sdwa v[92:93], v156 src0_sel:WORD_1
	v_cvt_pk_f32_fp8_e32 v[94:95], v157
	v_cvt_pk_f32_fp8_sdwa v[96:97], v157 src0_sel:WORD_1
	v_cvt_pk_f32_fp8_e32 v[100:101], v158
	v_cvt_pk_f32_fp8_sdwa v[102:103], v158 src0_sel:WORD_1
	v_cvt_pk_f32_fp8_e32 v[104:105], v159
	v_cvt_pk_f32_fp8_sdwa v[106:107], v159 src0_sel:WORD_1
	v_cvt_pk_f32_fp8_e32 v[108:109], v160
	v_cvt_pk_f32_fp8_sdwa v[110:111], v160 src0_sel:WORD_1
	v_cvt_pk_f32_fp8_e32 v[112:113], v161
	v_cvt_pk_f32_fp8_sdwa v[114:115], v161 src0_sel:WORD_1
	s_waitcnt vmcnt(12)
	v_cvt_pk_f32_fp8_e32 v[116:117], v36
	v_cvt_pk_f32_fp8_sdwa v[118:119], v36 src0_sel:WORD_1
	v_cvt_pk_f32_fp8_e32 v[120:121], v37
	v_cvt_pk_f32_fp8_sdwa v[36:37], v37 src0_sel:WORD_1
	v_cvt_pk_f32_fp8_e32 v[122:123], v38
	v_cvt_pk_f32_fp8_sdwa v[124:125], v38 src0_sel:WORD_1
	v_cvt_pk_f32_fp8_e32 v[126:127], v39
	v_cvt_pk_f32_fp8_sdwa v[38:39], v39 src0_sel:WORD_1
	v_lshlrev_b32_e32 v188, 16, v188
	v_cvt_pk_f32_fp8_e32 v[128:129], v40
	v_cvt_pk_f32_fp8_sdwa v[130:131], v40 src0_sel:WORD_1
	v_cvt_pk_f32_fp8_e32 v[132:133], v41
	v_cvt_pk_f32_fp8_sdwa v[40:41], v41 src0_sel:WORD_1
	v_cvt_pk_f32_fp8_e32 v[134:135], v42
	v_cvt_pk_f32_fp8_sdwa v[136:137], v42 src0_sel:WORD_1
	v_cvt_pk_f32_fp8_e32 v[154:155], v43
	v_cvt_pk_f32_fp8_sdwa v[42:43], v43 src0_sel:WORD_1
	s_waitcnt lgkmcnt(12)
	v_lshlrev_b32_e32 v190, 16, v190
	v_pk_fma_f32 v[60:61], v[82:83], v[188:189], v[60:61] op_sel_hi:[1,0,1]
	v_pk_fma_f32 v[62:63], v[84:85], v[188:189], v[62:63] op_sel_hi:[1,0,1]
	v_pk_fma_f32 v[64:65], v[86:87], v[188:189], v[64:65] op_sel_hi:[1,0,1]
	v_pk_fma_f32 v[66:67], v[88:89], v[188:189], v[66:67] op_sel_hi:[1,0,1]
	v_pk_fma_f32 v[68:69], v[90:91], v[188:189], v[68:69] op_sel_hi:[1,0,1]
	v_pk_fma_f32 v[70:71], v[92:93], v[188:189], v[70:71] op_sel_hi:[1,0,1]
	v_pk_fma_f32 v[78:79], v[94:95], v[188:189], v[78:79] op_sel_hi:[1,0,1]
	v_pk_fma_f32 v[80:81], v[96:97], v[188:189], v[80:81] op_sel_hi:[1,0,1]
	s_waitcnt vmcnt(11)
	v_cvt_pk_f32_fp8_e32 v[82:83], v44
	v_cvt_pk_f32_fp8_sdwa v[84:85], v44 src0_sel:WORD_1
	v_cvt_pk_f32_fp8_e32 v[86:87], v45
	v_cvt_pk_f32_fp8_sdwa v[44:45], v45 src0_sel:WORD_1
	v_cvt_pk_f32_fp8_e32 v[88:89], v46
	v_cvt_pk_f32_fp8_sdwa v[90:91], v46 src0_sel:WORD_1
	v_cvt_pk_f32_fp8_e32 v[92:93], v47
	v_cvt_pk_f32_fp8_sdwa v[46:47], v47 src0_sel:WORD_1
	v_lshlrev_b32_e32 v192, 16, v192
	v_pk_fma_f32 v[60:61], v[100:101], v[190:191], v[60:61] op_sel_hi:[1,0,1]
	v_pk_fma_f32 v[62:63], v[102:103], v[190:191], v[62:63] op_sel_hi:[1,0,1]
	v_pk_fma_f32 v[64:65], v[104:105], v[190:191], v[64:65] op_sel_hi:[1,0,1]
	v_pk_fma_f32 v[66:67], v[106:107], v[190:191], v[66:67] op_sel_hi:[1,0,1]
	v_pk_fma_f32 v[68:69], v[108:109], v[190:191], v[68:69] op_sel_hi:[1,0,1]
	v_pk_fma_f32 v[70:71], v[110:111], v[190:191], v[70:71] op_sel_hi:[1,0,1]
	v_pk_fma_f32 v[78:79], v[112:113], v[190:191], v[78:79] op_sel_hi:[1,0,1]
	v_pk_fma_f32 v[80:81], v[114:115], v[190:191], v[80:81] op_sel_hi:[1,0,1]
	s_waitcnt vmcnt(10)
	v_cvt_pk_f32_fp8_e32 v[94:95], v48
	v_cvt_pk_f32_fp8_sdwa v[96:97], v48 src0_sel:WORD_1
	v_cvt_pk_f32_fp8_e32 v[100:101], v49
	v_cvt_pk_f32_fp8_sdwa v[48:49], v49 src0_sel:WORD_1
	v_cvt_pk_f32_fp8_e32 v[102:103], v50
	v_cvt_pk_f32_fp8_sdwa v[104:105], v50 src0_sel:WORD_1
	v_cvt_pk_f32_fp8_e32 v[106:107], v51
	v_cvt_pk_f32_fp8_sdwa v[50:51], v51 src0_sel:WORD_1
	s_waitcnt lgkmcnt(10)
	v_lshlrev_b32_e32 v194, 16, v193
	v_pk_fma_f32 v[60:61], v[116:117], v[192:193], v[60:61] op_sel_hi:[1,0,1]
	v_pk_fma_f32 v[62:63], v[118:119], v[192:193], v[62:63] op_sel_hi:[1,0,1]
	v_pk_fma_f32 v[64:65], v[120:121], v[192:193], v[64:65] op_sel_hi:[1,0,1]
	v_pk_fma_f32 v[36:37], v[36:37], v[192:193], v[66:67] op_sel_hi:[1,0,1]
	v_pk_fma_f32 v[66:67], v[122:123], v[192:193], v[68:69] op_sel_hi:[1,0,1]
	v_pk_fma_f32 v[68:69], v[124:125], v[192:193], v[70:71] op_sel_hi:[1,0,1]
	v_pk_fma_f32 v[70:71], v[126:127], v[192:193], v[78:79] op_sel_hi:[1,0,1]
	v_pk_fma_f32 v[38:39], v[38:39], v[192:193], v[80:81] op_sel_hi:[1,0,1]
	s_waitcnt vmcnt(8)
	v_cvt_pk_f32_fp8_e32 v[78:79], v52
	v_cvt_pk_f32_fp8_sdwa v[80:81], v52 src0_sel:WORD_1
	v_cvt_pk_f32_fp8_e32 v[108:109], v53
	v_cvt_pk_f32_fp8_sdwa v[52:53], v53 src0_sel:WORD_1
	v_cvt_pk_f32_fp8_e32 v[110:111], v54
	v_cvt_pk_f32_fp8_sdwa v[112:113], v54 src0_sel:WORD_1
	v_cvt_pk_f32_fp8_e32 v[114:115], v55
	v_cvt_pk_f32_fp8_sdwa v[54:55], v55 src0_sel:WORD_1
	v_lshlrev_b32_e32 v196, 16, v195
	v_pk_fma_f32 v[60:61], v[128:129], v[194:195], v[60:61] op_sel_hi:[1,0,1]
	v_pk_fma_f32 v[62:63], v[130:131], v[194:195], v[62:63] op_sel_hi:[1,0,1]
	v_pk_fma_f32 v[64:65], v[132:133], v[194:195], v[64:65] op_sel_hi:[1,0,1]
	v_pk_fma_f32 v[36:37], v[40:41], v[194:195], v[36:37] op_sel_hi:[1,0,1]
	v_pk_fma_f32 v[40:41], v[134:135], v[194:195], v[66:67] op_sel_hi:[1,0,1]
	v_pk_fma_f32 v[66:67], v[136:137], v[194:195], v[68:69] op_sel_hi:[1,0,1]
	v_pk_fma_f32 v[68:69], v[154:155], v[194:195], v[70:71] op_sel_hi:[1,0,1]
	v_pk_fma_f32 v[38:39], v[42:43], v[194:195], v[38:39] op_sel_hi:[1,0,1]
	v_cvt_pk_f32_fp8_e32 v[42:43], v56
	v_cvt_pk_f32_fp8_sdwa v[70:71], v56 src0_sel:WORD_1
	v_cvt_pk_f32_fp8_e32 v[116:117], v57
	v_cvt_pk_f32_fp8_sdwa v[56:57], v57 src0_sel:WORD_1
	v_cvt_pk_f32_fp8_e32 v[118:119], v58
	v_cvt_pk_f32_fp8_sdwa v[120:121], v58 src0_sel:WORD_1
	v_cvt_pk_f32_fp8_e32 v[122:123], v59
	v_cvt_pk_f32_fp8_sdwa v[58:59], v59 src0_sel:WORD_1
	s_waitcnt lgkmcnt(8)
	v_lshlrev_b32_e32 v198, 16, v197
	v_pk_fma_f32 v[60:61], v[82:83], v[196:197], v[60:61] op_sel_hi:[1,0,1]
	v_pk_fma_f32 v[62:63], v[84:85], v[196:197], v[62:63] op_sel_hi:[1,0,1]
	v_pk_fma_f32 v[64:65], v[86:87], v[196:197], v[64:65] op_sel_hi:[1,0,1]
	v_pk_fma_f32 v[36:37], v[44:45], v[196:197], v[36:37] op_sel_hi:[1,0,1]
	v_pk_fma_f32 v[40:41], v[88:89], v[196:197], v[40:41] op_sel_hi:[1,0,1]
	v_pk_fma_f32 v[44:45], v[90:91], v[196:197], v[66:67] op_sel_hi:[1,0,1]
	v_pk_fma_f32 v[66:67], v[92:93], v[196:197], v[68:69] op_sel_hi:[1,0,1]
	v_pk_fma_f32 v[38:39], v[46:47], v[196:197], v[38:39] op_sel_hi:[1,0,1]
	v_lshlrev_b32_e32 v200, 16, v199
	v_pk_fma_f32 v[46:47], v[94:95], v[198:199], v[60:61] op_sel_hi:[1,0,1]
	v_pk_fma_f32 v[60:61], v[96:97], v[198:199], v[62:63] op_sel_hi:[1,0,1]
	v_pk_fma_f32 v[62:63], v[100:101], v[198:199], v[64:65] op_sel_hi:[1,0,1]
	v_pk_fma_f32 v[36:37], v[48:49], v[198:199], v[36:37] op_sel_hi:[1,0,1]
	v_pk_fma_f32 v[40:41], v[102:103], v[198:199], v[40:41] op_sel_hi:[1,0,1]
	v_pk_fma_f32 v[44:45], v[104:105], v[198:199], v[44:45] op_sel_hi:[1,0,1]
	v_pk_fma_f32 v[48:49], v[106:107], v[198:199], v[66:67] op_sel_hi:[1,0,1]
	v_pk_fma_f32 v[38:39], v[50:51], v[198:199], v[38:39] op_sel_hi:[1,0,1]
	s_waitcnt lgkmcnt(7)
	v_lshlrev_b32_e32 v202, 16, v201
	v_pk_fma_f32 v[46:47], v[78:79], v[200:201], v[46:47] op_sel_hi:[1,0,1]
	v_pk_fma_f32 v[50:51], v[80:81], v[200:201], v[60:61] op_sel_hi:[1,0,1]
	v_pk_fma_f32 v[60:61], v[108:109], v[200:201], v[62:63] op_sel_hi:[1,0,1]
	v_pk_fma_f32 v[36:37], v[52:53], v[200:201], v[36:37] op_sel_hi:[1,0,1]
	v_pk_fma_f32 v[40:41], v[110:111], v[200:201], v[40:41] op_sel_hi:[1,0,1]
	v_pk_fma_f32 v[44:45], v[112:113], v[200:201], v[44:45] op_sel_hi:[1,0,1]
	v_pk_fma_f32 v[48:49], v[114:115], v[200:201], v[48:49] op_sel_hi:[1,0,1]
	v_pk_fma_f32 v[38:39], v[54:55], v[200:201], v[38:39] op_sel_hi:[1,0,1]
	v_pk_fma_f32 v[42:43], v[42:43], v[202:203], v[46:47] op_sel_hi:[1,0,1]
	v_pk_fma_f32 v[46:47], v[70:71], v[202:203], v[50:51] op_sel_hi:[1,0,1]
	v_pk_fma_f32 v[50:51], v[116:117], v[202:203], v[60:61] op_sel_hi:[1,0,1]
	v_pk_fma_f32 v[36:37], v[56:57], v[202:203], v[36:37] op_sel_hi:[1,0,1]
	v_pk_fma_f32 v[40:41], v[118:119], v[202:203], v[40:41] op_sel_hi:[1,0,1]
	v_pk_fma_f32 v[44:45], v[120:121], v[202:203], v[44:45] op_sel_hi:[1,0,1]
	v_pk_fma_f32 v[48:49], v[122:123], v[202:203], v[48:49] op_sel_hi:[1,0,1]
	v_pk_fma_f32 v[38:39], v[58:59], v[202:203], v[38:39] op_sel_hi:[1,0,1]
	v_lshlrev_b32_e32 v98, 16, v203
	v_and_b32_e32 v99, 0xffff0000, v203
	v_permlane32_swap_b32 v42, v40
	v_permlane32_swap_b32 v43, v41
	v_permlane32_swap_b32 v46, v44
	v_permlane32_swap_b32 v47, v45
	v_permlane32_swap_b32 v50, v48
	v_permlane32_swap_b32 v51, v49
	v_permlane32_swap_b32 v36, v38
	v_permlane32_swap_b32 v37, v39
	s_add_i32 s7, s41, 1
	v_pk_add_f32 v[166:167], v[166:167], s[100:101] op_sel_hi:[1,0] neg_lo:[0,1] neg_hi:[0,1]
	v_pk_add_f32 v[40:41], v[42:43], v[40:41]
	v_pk_add_f32 v[44:45], v[46:47], v[44:45]
	v_pk_mul_f32 v[166:167], v[166:167], s[100:101] op_sel:[0,1]
	v_pk_add_f32 v[48:49], v[50:51], v[48:49]
	v_pk_add_f32 v[38:39], v[36:37], v[38:39]
	v_pk_fma_f32 v[166:167], v[246:247], v[166:167], v[248:249]
	s_addk_i32 s6, 0x80
	v_permlane16_swap_b32 v40, v48
	v_permlane16_swap_b32 v41, v49
	v_permlane16_swap_b32 v44, v38
	v_permlane16_swap_b32 v45, v39
	v_pk_fma_f32 v[98:99], v[166:167], s[58:59], v[98:99] op_sel_hi:[1,0,1]
	v_pk_add_f32 v[36:37], v[44:45], v[38:39]
	v_pk_add_f32 v[38:39], v[40:41], v[48:49]
	s_add_i32 s3, s3, 0x10000
	v_cndmask_b32_e64 v40, v38, v36, s[0:1]
	v_cndmask_b32_e64 v41, v39, v37, s[0:1]
	v_cndmask_b32_e64 v37, v37, v39, s[0:1]
	v_cndmask_b32_e64 v36, v36, v38, s[0:1]
	v_mov_b32_dpp v38, v40 row_ror:8 row_mask:0xf bank_mask:0xf bound_ctrl:1
	v_mov_b32_dpp v39, v41 row_ror:8 row_mask:0xf bank_mask:0xf bound_ctrl:1
	s_mov_b32 s41, s7
	s_cmpk_eq_i32 s7, 0x100
	v_pk_add_f32 v[36:37], v[36:37], v[38:39]
	s_nop 0
	v_pk_add_f32 v[36:37], v[98:99], v[36:37]
	global_store_dwordx2 v[138:139], v[36:37], off
	s_cbranch_scc0 .LBB0_1139
	s_waitcnt vmcnt(0)
	s_barrier
	v_lshlrev_b64 v[0:1], 12, v[74:75]
	v_lshl_add_u64 v[0:1], s[60:61], 0, v[0:1]
	v_mov_b32_e32 v77, v73
	v_lshl_add_u64 v[64:65], v[0:1], 0, v[76:77]
	v_lshl_add_u64 v[66:67], s[90:91], 0, v[76:77]
	v_lshl_add_u64 v[68:69], s[68:69], 0, v[76:77]
	s_mov_b64 s[100:101], 0x1000
	v_lshl_add_u64 v[64:65], v[64:65], 0, s[100:101]
	global_load_dwordx4 v[206:209], v[66:67], off
	global_load_dwordx4 v[210:213], v[66:67], off offset:1024
	global_load_dwordx4 v[214:217], v[66:67], off offset:2048
	global_load_dwordx4 v[218:221], v[66:67], off offset:3072
	global_load_dwordx4 v[222:225], v[68:69], off
	global_load_dwordx4 v[226:229], v[68:69], off offset:1024
	global_load_dwordx4 v[230:233], v[68:69], off offset:2048
	global_load_dwordx4 v[234:237], v[68:69], off offset:3072
	global_load_dwordx4 v[0:3], v[64:65], off offset:-4096
	global_load_dwordx4 v[4:7], v[64:65], off offset:-3072
	global_load_dwordx4 v[8:11], v[64:65], off offset:-2048
	global_load_dwordx4 v[12:15], v[64:65], off offset:-1024
	global_load_dwordx4 v[40:43], v[66:67], off
	global_load_dwordx4 v[40:43], v[66:67], off
	global_load_dwordx4 v[40:43], v[66:67], off
	global_load_dwordx4 v[40:43], v[66:67], off
	s_mov_b32 s0, 0
